# nt cache hint on the one-shot residual-row loads in the ffn2 and merge2 epilogues (keep GEMM operands in L2), on v27
# speedup vs baseline: 1.0618x; 1.0618x over previous
.LBB0_139:
	v_cmp_eq_u32_e32 vcc, s14, v73
	s_lshl_b32 s15, s14, 6
	v_lshrrev_b32_e32 v75, 5, v72
	v_add_u32_e32 v76, s15, v75
	v_mov_b32_e32 v77, 0
	v_mad_u32_u24 v101, v75, s48, v148
	v_lshlrev_b64 v[80:81], 12, v[76:77]
	v_lshlrev_b32_e32 v76, 1, v76
	v_lshl_add_u64 v[98:99], v[64:65], 0, v[80:81]
	v_lshl_add_u64 v[76:77], v[76:77], 2, s[22:23]
	s_mov_b64 s[16:17], 0x8000
	v_mov_b64_e32 v[82:83], v[98:99]
	global_load_dwordx2 v[172:173], v[76:77], off
	global_load_dwordx4 v[188:191], v[82:83], off nt
	v_lshl_add_u64 v[82:83], v[82:83], 0, s[16:17]
	global_load_dwordx2 v[174:175], v[76:77], off offset:64
	global_load_dwordx4 v[192:195], v[82:83], off nt
	v_lshl_add_u64 v[82:83], v[82:83], 0, s[16:17]
	global_load_dwordx2 v[176:177], v[76:77], off offset:128
	global_load_dwordx4 v[196:199], v[82:83], off nt
	v_lshl_add_u64 v[82:83], v[82:83], 0, s[16:17]
	global_load_dwordx2 v[178:179], v[76:77], off offset:192
	global_load_dwordx4 v[200:203], v[82:83], off nt
	v_lshl_add_u64 v[82:83], v[82:83], 0, s[16:17]
	global_load_dwordx2 v[180:181], v[76:77], off offset:256
	global_load_dwordx4 v[204:207], v[82:83], off nt
	v_lshl_add_u64 v[82:83], v[82:83], 0, s[16:17]
	global_load_dwordx2 v[182:183], v[76:77], off offset:320
	global_load_dwordx4 v[208:211], v[82:83], off nt
	v_lshl_add_u64 v[82:83], v[82:83], 0, s[16:17]
	global_load_dwordx2 v[184:185], v[76:77], off offset:384
	global_load_dwordx4 v[212:215], v[82:83], off nt
	v_lshl_add_u64 v[82:83], v[82:83], 0, s[16:17]
	global_load_dwordx2 v[186:187], v[76:77], off offset:448
	global_load_dwordx4 v[216:219], v[82:83], off nt
	s_barrier
	s_and_saveexec_b64 s[28:29], vcc
	s_cbranch_execz .LBB0_141
	v_add_u32_e32 v75, 0x8000, v74
	v_add_u32_e32 v76, 0x8400, v74
	ds_write2_b32 v75, v52, v48 offset1:16
	ds_write2_b32 v75, v53, v49 offset0:132 offset1:148
	ds_write2_b32 v76, v54, v50 offset0:8 offset1:24
	ds_write2_b32 v76, v55, v51 offset0:140 offset1:156
	ds_write2_b32 v75, v44, v40 offset0:32 offset1:48
	ds_write2_b32 v75, v45, v41 offset0:164 offset1:180
	ds_write2_b32 v76, v46, v42 offset0:40 offset1:56
	ds_write2_b32 v76, v47, v43 offset0:172 offset1:188
	v_add_u32_e32 v75, 0xa000, v74
	v_add_u32_e32 v76, 0xa400, v74
	ds_write2_b32 v75, v36, v32 offset0:64 offset1:80
	ds_write2_b32 v75, v37, v33 offset0:196 offset1:212
	ds_write2_b32 v76, v38, v34 offset0:72 offset1:88
	ds_write2_b32 v76, v39, v35 offset0:204 offset1:220
	ds_write2_b32 v75, v28, v24 offset0:96 offset1:112
	ds_write2_b32 v75, v29, v25 offset0:228 offset1:244
	ds_write2_b32 v76, v30, v26 offset0:104 offset1:120
	ds_write2_b32 v76, v31, v27 offset0:236 offset1:252
	v_add_u32_e32 v75, 0xc000, v74
	v_add_u32_e32 v76, 0xc400, v74
	v_add_u32_e32 v77, 0xc800, v74
	ds_write2_b32 v75, v20, v16 offset0:128 offset1:144
	ds_write2_b32 v76, v21, v17 offset0:4 offset1:20
	ds_write2_b32 v76, v22, v18 offset0:136 offset1:152
	ds_write2_b32 v77, v23, v19 offset0:12 offset1:28
	ds_write2_b32 v75, v12, v8 offset0:160 offset1:176
	ds_write2_b32 v76, v13, v9 offset0:36 offset1:52
	ds_write2_b32 v76, v14, v10 offset0:168 offset1:184
	ds_write2_b32 v77, v15, v11 offset0:44 offset1:60
	v_add_u32_e32 v75, 0xe000, v74
	v_add_u32_e32 v76, 0xe400, v74
	v_add_u32_e32 v77, 0xe800, v74
	ds_write2_b32 v75, v4, v0 offset0:192 offset1:208
	ds_write2_b32 v76, v5, v1 offset0:68 offset1:84
	ds_write2_b32 v76, v6, v2 offset0:200 offset1:216
	ds_write2_b32 v77, v7, v3 offset0:76 offset1:92
	ds_write2_b32 v75, v56, v60 offset0:224 offset1:240
	ds_write2_b32 v76, v57, v61 offset0:100 offset1:116
	ds_write2_b32 v76, v58, v62 offset0:232 offset1:248
	ds_write2_b32 v77, v59, v63 offset0:108 offset1:124

.LBB0_273:
	v_cmp_eq_u32_e32 vcc, s14, v90
	s_lshl_b32 s15, s14, 6
	v_lshrrev_b32_e32 v92, 5, v89
	v_add_u32_e32 v94, s15, v92
	v_mov_b32_e32 v95, 0
	v_mad_u32_u24 v93, v92, s48, v148
	v_lshlrev_b64 v[96:97], 12, v[94:95]
	v_lshlrev_b32_e32 v94, 1, v94
	v_lshl_add_u64 v[98:99], v[80:81], 0, v[96:97]
	v_lshl_add_u64 v[100:101], v[76:77], 0, v[96:97]
	v_lshl_add_u64 v[102:103], v[94:95], 2, s[30:31]
	s_mov_b64 s[16:17], 0x8000
	global_load_dwordx2 v[172:173], v[102:103], off
	global_load_dwordx4 v[188:191], v[100:101], off nt
	v_lshl_add_u64 v[100:101], v[100:101], 0, s[16:17]
	global_load_dwordx2 v[174:175], v[102:103], off offset:64
	global_load_dwordx4 v[192:195], v[100:101], off nt
	v_lshl_add_u64 v[100:101], v[100:101], 0, s[16:17]
	global_load_dwordx2 v[176:177], v[102:103], off offset:128
	global_load_dwordx4 v[196:199], v[100:101], off nt
	v_lshl_add_u64 v[100:101], v[100:101], 0, s[16:17]
	global_load_dwordx2 v[178:179], v[102:103], off offset:192
	global_load_dwordx4 v[200:203], v[100:101], off nt
	v_lshl_add_u64 v[100:101], v[100:101], 0, s[16:17]
	global_load_dwordx2 v[180:181], v[102:103], off offset:256
	global_load_dwordx4 v[204:207], v[100:101], off nt
	v_lshl_add_u64 v[100:101], v[100:101], 0, s[16:17]
	global_load_dwordx2 v[182:183], v[102:103], off offset:320
	global_load_dwordx4 v[208:211], v[100:101], off nt
	v_lshl_add_u64 v[100:101], v[100:101], 0, s[16:17]
	global_load_dwordx2 v[184:185], v[102:103], off offset:384
	global_load_dwordx4 v[212:215], v[100:101], off nt
	v_lshl_add_u64 v[100:101], v[100:101], 0, s[16:17]
	global_load_dwordx2 v[186:187], v[102:103], off offset:448
	global_load_dwordx4 v[216:219], v[100:101], off nt
	s_barrier
	s_and_saveexec_b64 s[36:37], vcc
	s_cbranch_execz .LBB0_275
	v_add_u32_e32 v64, 0x8000, v91
	v_add_u32_e32 v65, 0x8400, v91
	ds_write2_b32 v64, v44, v40 offset1:16
	ds_write2_b32 v64, v45, v41 offset0:132 offset1:148
	ds_write2_b32 v65, v46, v42 offset0:8 offset1:24
	ds_write2_b32 v65, v47, v43 offset0:140 offset1:156
	ds_write2_b32 v64, v36, v32 offset0:32 offset1:48
	ds_write2_b32 v64, v37, v33 offset0:164 offset1:180
	ds_write2_b32 v65, v38, v34 offset0:40 offset1:56
	ds_write2_b32 v65, v39, v35 offset0:172 offset1:188
	v_add_u32_e32 v64, 0xa000, v91
	v_add_u32_e32 v65, 0xa400, v91
	ds_write2_b32 v64, v28, v24 offset0:64 offset1:80
	ds_write2_b32 v64, v29, v25 offset0:196 offset1:212
	ds_write2_b32 v65, v30, v26 offset0:72 offset1:88
	ds_write2_b32 v65, v31, v27 offset0:204 offset1:220
	ds_write2_b32 v64, v20, v16 offset0:96 offset1:112
	ds_write2_b32 v64, v21, v17 offset0:228 offset1:244
	ds_write2_b32 v65, v22, v18 offset0:104 offset1:120
	ds_write2_b32 v65, v23, v19 offset0:236 offset1:252
	v_add_u32_e32 v64, 0xc000, v91
	v_add_u32_e32 v65, 0xc400, v91
	v_add_u32_e32 v66, 0xc800, v91
	ds_write2_b32 v64, v12, v8 offset0:128 offset1:144
	ds_write2_b32 v65, v13, v9 offset0:4 offset1:20
	ds_write2_b32 v65, v14, v10 offset0:136 offset1:152
	ds_write2_b32 v66, v15, v11 offset0:12 offset1:28
	ds_write2_b32 v64, v4, v0 offset0:160 offset1:176
	ds_write2_b32 v65, v5, v1 offset0:36 offset1:52
	ds_write2_b32 v65, v6, v2 offset0:168 offset1:184
	ds_write2_b32 v66, v7, v3 offset0:44 offset1:60
	v_add_u32_e32 v64, 0xe000, v91
	v_add_u32_e32 v65, 0xe400, v91
	v_add_u32_e32 v66, 0xe800, v91
	ds_write2_b32 v64, v48, v52 offset0:192 offset1:208
	ds_write2_b32 v65, v49, v53 offset0:68 offset1:84
	ds_write2_b32 v65, v50, v54 offset0:200 offset1:216
	ds_write2_b32 v66, v51, v55 offset0:76 offset1:92
	ds_write2_b32 v64, v56, v60 offset0:224 offset1:240
	ds_write2_b32 v65, v57, v61 offset0:100 offset1:116
	ds_write2_b32 v65, v58, v62 offset0:232 offset1:248
	ds_write2_b32 v66, v59, v63 offset0:108 offset1:124
